# pk2
# speedup vs baseline: 1.0068x; 1.0068x over previous
; __device__ __forceinline__ u16 f2bf(float x) { return (u16)(cvtpk(x, x) & 0xffffu); }
; #define UNR _Pragma("unroll")
; template <int EPI, int lda, int ldb, int N, int K>
; __device__ __forceinline__ void gemm_phase(const u16* __restrict__ A, const u16* __restrict__ Bt, const GemmEpi ep, int wv) {
;     ...
;     if constexpr (EPI == EPI_SWIGLU) {
;       u16* out = reinterpret_cast<u16*>(ep.out0);
;       UNR for (int ai = 0; ai < 2; ++ai) UNR for (int m = 0; m < 4; ++m) {
;         const int rl0 = ai * HALF + wr * 64 + m * 16 + fq * 4;
;         const f32x4 r4 = *reinterpret_cast<const f32x4*>(lrs + rl0);
;         UNR for (int j = 0; j < 4; ++j) {
;           const int row = brow + rl0 + j;
;           const float rs = r4[j], ce = -1.4426950408889634f * rs, r2 = rs * rs;
;           UNR for (int n = 0; n < 2; ++n) {
;             const int col = (bcol >> 1) + wc * 32 + n * 16 + fr;
;             const float g = acc[ai][0][m][n][j], u = acc[ai][1][m][n][j];
;             const float sg = __builtin_amdgcn_rcpf(1.f + __builtin_amdgcn_exp2f(ce * g));
;             out[(size_t)row * ep.ldc + col] = f2bf((g * u) * (r2 * sg));
;           }
;         }
;       }
.LBB0_60:
	s_or_b64 exec, exec, s[48:49]
	v_and_b32_e32 v132, 15, v130
	v_lshrrev_b32_e32 v134, 8, v130
	v_lshl_add_u32 v132, v134, 6, v132
	v_lshlrev_b32_e32 v149, 2, v132
	v_add_u32_e32 v149, 0x20000, v149
	ds_read_b32 v150, v149 offset:0
	ds_read_b32 v151, v149 offset:64
	ds_read_b32 v152, v149 offset:128
	ds_read_b32 v153, v149 offset:192
	v_add_u32_e32 v132, s38, v132
	v_mul_u32_u24_e32 v135, 0x2b00, v132
	v_bfe_u32 v134, v130, 6, 2
	v_lshlrev_b32_e32 v134, 5, v134
	v_bfe_u32 v132, v130, 4, 1
	v_lshl_add_u32 v134, v132, 4, v134
	v_bfe_u32 v132, v130, 5, 1
	v_lshl_add_u32 v134, v132, 3, v134
	v_lshrrev_b32_e64 v132, 1, s39
	v_add_u32_e32 v134, v132, v134
	v_lshl_add_u32 v135, v134, 1, v135
	s_waitcnt lgkmcnt(0)
	v_mul_f32_e32 v132, 0xbfb8aa3b, v150
	v_mul_f32_e32 v134, v150, v150
	ds_read_b32 v150, v149 offset:512
	v_pk_mul_f32 v[124:125], v[116:117], v[124:125]
	v_pk_mul_f32 v[116:117], v[116:117], v[132:133] op_sel_hi:[1,0]
	v_pk_mul_f32 v[126:127], v[118:119], v[126:127]
	v_pk_mul_f32 v[118:119], v[118:119], v[132:133] op_sel_hi:[1,0]
	v_exp_f32_e32 v116, v116
	v_exp_f32_e32 v117, v117
	v_exp_f32_e32 v118, v118
	v_exp_f32_e32 v119, v119
	v_pk_add_f32 v[116:117], v[116:117], 1.0 op_sel_hi:[1,0]
	v_pk_add_f32 v[118:119], v[118:119], 1.0 op_sel_hi:[1,0]
	v_rcp_f32_e32 v116, v116
	v_rcp_f32_e32 v117, v117
	v_rcp_f32_e32 v118, v118
	v_rcp_f32_e32 v119, v119
	v_pk_mul_f32 v[116:117], v[116:117], v[134:135] op_sel_hi:[1,0]
	v_pk_mul_f32 v[118:119], v[118:119], v[134:135] op_sel_hi:[1,0]
	v_pk_mul_f32 v[124:125], v[124:125], v[116:117]
	v_pk_mul_f32 v[126:127], v[126:127], v[118:119]
	v_cvt_pk_bf16_f32 v116, v124, v125
	v_cvt_pk_bf16_f32 v117, v126, v127
	v_pk_mul_f32 v[120:121], v[112:113], v[120:121]
	v_pk_mul_f32 v[112:113], v[112:113], v[132:133] op_sel_hi:[1,0]
	v_pk_mul_f32 v[122:123], v[114:115], v[122:123]
	v_pk_mul_f32 v[114:115], v[114:115], v[132:133] op_sel_hi:[1,0]
	v_exp_f32_e32 v112, v112
	v_exp_f32_e32 v113, v113
	v_exp_f32_e32 v114, v114
	v_exp_f32_e32 v115, v115
	v_pk_add_f32 v[112:113], v[112:113], 1.0 op_sel_hi:[1,0]
	v_pk_add_f32 v[114:115], v[114:115], 1.0 op_sel_hi:[1,0]
	v_rcp_f32_e32 v112, v112
	v_rcp_f32_e32 v113, v113
	v_rcp_f32_e32 v114, v114
	v_rcp_f32_e32 v115, v115
	v_pk_mul_f32 v[112:113], v[112:113], v[134:135] op_sel_hi:[1,0]
	v_pk_mul_f32 v[114:115], v[114:115], v[134:135] op_sel_hi:[1,0]
	v_pk_mul_f32 v[120:121], v[120:121], v[112:113]
	v_pk_mul_f32 v[122:123], v[122:123], v[114:115]
	v_cvt_pk_bf16_f32 v118, v120, v121
	v_cvt_pk_bf16_f32 v119, v122, v123
	s_nop 1
	v_permlane16_swap_b32_e32 v116, v118
	v_permlane16_swap_b32_e32 v117, v119
	global_store_dwordx4 v135, v[116:119], s[10:11]
	v_add_u32_e32 v133, 0x2b000, v135
	v_mul_f32_e32 v132, 0xbfb8aa3b, v151
	v_mul_f32_e32 v134, v151, v151
	ds_read_b32 v151, v149 offset:576
	v_pk_mul_f32 v[108:109], v[100:101], v[108:109]
	v_pk_mul_f32 v[100:101], v[100:101], v[132:133] op_sel_hi:[1,0]
	v_pk_mul_f32 v[110:111], v[102:103], v[110:111]
	v_pk_mul_f32 v[102:103], v[102:103], v[132:133] op_sel_hi:[1,0]
	v_exp_f32_e32 v100, v100
	v_exp_f32_e32 v101, v101
	v_exp_f32_e32 v102, v102
	v_exp_f32_e32 v103, v103
	v_pk_add_f32 v[100:101], v[100:101], 1.0 op_sel_hi:[1,0]
	v_pk_add_f32 v[102:103], v[102:103], 1.0 op_sel_hi:[1,0]
	v_rcp_f32_e32 v100, v100
	v_rcp_f32_e32 v101, v101
	v_rcp_f32_e32 v102, v102
	v_rcp_f32_e32 v103, v103
	v_pk_mul_f32 v[100:101], v[100:101], v[134:135] op_sel_hi:[1,0]
	v_pk_mul_f32 v[102:103], v[102:103], v[134:135] op_sel_hi:[1,0]
	v_pk_mul_f32 v[108:109], v[108:109], v[100:101]
	v_pk_mul_f32 v[110:111], v[110:111], v[102:103]
	v_cvt_pk_bf16_f32 v100, v108, v109
	v_cvt_pk_bf16_f32 v101, v110, v111
	v_pk_mul_f32 v[104:105], v[96:97], v[104:105]
	v_pk_mul_f32 v[96:97], v[96:97], v[132:133] op_sel_hi:[1,0]
	v_pk_mul_f32 v[106:107], v[98:99], v[106:107]
	v_pk_mul_f32 v[98:99], v[98:99], v[132:133] op_sel_hi:[1,0]
	v_exp_f32_e32 v96, v96
	v_exp_f32_e32 v97, v97
	v_exp_f32_e32 v98, v98
	v_exp_f32_e32 v99, v99
	v_pk_add_f32 v[96:97], v[96:97], 1.0 op_sel_hi:[1,0]
	v_pk_add_f32 v[98:99], v[98:99], 1.0 op_sel_hi:[1,0]
	v_rcp_f32_e32 v96, v96
	v_rcp_f32_e32 v97, v97
	v_rcp_f32_e32 v98, v98
	v_rcp_f32_e32 v99, v99
	v_pk_mul_f32 v[96:97], v[96:97], v[134:135] op_sel_hi:[1,0]
	v_pk_mul_f32 v[98:99], v[98:99], v[134:135] op_sel_hi:[1,0]
	v_pk_mul_f32 v[104:105], v[104:105], v[96:97]
	v_pk_mul_f32 v[106:107], v[106:107], v[98:99]
	v_cvt_pk_bf16_f32 v102, v104, v105
	v_cvt_pk_bf16_f32 v103, v106, v107
	s_nop 1
	v_permlane16_swap_b32_e32 v100, v102
	v_permlane16_swap_b32_e32 v101, v103
	global_store_dwordx4 v133, v[100:103], s[10:11]
	v_add_u32_e32 v133, 0x56000, v135
	v_mul_f32_e32 v132, 0xbfb8aa3b, v152
	v_mul_f32_e32 v134, v152, v152
	ds_read_b32 v152, v149 offset:640
	v_pk_mul_f32 v[92:93], v[84:85], v[92:93]
	v_pk_mul_f32 v[84:85], v[84:85], v[132:133] op_sel_hi:[1,0]
	v_pk_mul_f32 v[94:95], v[86:87], v[94:95]
	v_pk_mul_f32 v[86:87], v[86:87], v[132:133] op_sel_hi:[1,0]
	v_exp_f32_e32 v84, v84
	v_exp_f32_e32 v85, v85
	v_exp_f32_e32 v86, v86
	v_exp_f32_e32 v87, v87
	v_pk_add_f32 v[84:85], v[84:85], 1.0 op_sel_hi:[1,0]
	v_pk_add_f32 v[86:87], v[86:87], 1.0 op_sel_hi:[1,0]
	v_rcp_f32_e32 v84, v84
	v_rcp_f32_e32 v85, v85
	v_rcp_f32_e32 v86, v86
	v_rcp_f32_e32 v87, v87
	v_pk_mul_f32 v[84:85], v[84:85], v[134:135] op_sel_hi:[1,0]
	v_pk_mul_f32 v[86:87], v[86:87], v[134:135] op_sel_hi:[1,0]
	v_pk_mul_f32 v[92:93], v[92:93], v[84:85]
	v_pk_mul_f32 v[94:95], v[94:95], v[86:87]
	v_cvt_pk_bf16_f32 v84, v92, v93
	v_cvt_pk_bf16_f32 v85, v94, v95
	v_pk_mul_f32 v[88:89], v[80:81], v[88:89]
	v_pk_mul_f32 v[80:81], v[80:81], v[132:133] op_sel_hi:[1,0]
; __device__ __forceinline__ u16 f2bf(float x) { return (u16)(cvtpk(x, x) & 0xffffu); }
; #define UNR _Pragma("unroll")
; template <int EPI, int lda, int ldb, int N, int K>
; __device__ __forceinline__ void gemm_phase(const u16* __restrict__ A, const u16* __restrict__ Bt, const GemmEpi ep, int wv) {
;     ...
;       UNR for (int ai = 0; ai < 2; ++ai) UNR for (int m = 0; m < 4; ++m) {
;         const int rl0 = ai * HALF + wr * 64 + m * 16 + fq * 4;
;         const f32x4 r4 = *reinterpret_cast<const f32x4*>(lrs + rl0);
;         UNR for (int j = 0; j < 4; ++j) {
;           const int row = brow + rl0 + j;
;           const float rs = r4[j], ce = -1.4426950408889634f * rs, r2 = rs * rs;
;           UNR for (int n = 0; n < 2; ++n) {
;             const int col = (bcol >> 1) + wc * 32 + n * 16 + fr;
;             const float g = acc[ai][0][m][n][j], u = acc[ai][1][m][n][j];
;             const float sg = __builtin_amdgcn_rcpf(1.f + __builtin_amdgcn_exp2f(ce * g));
;             out[(size_t)row * ep.ldc + col] = f2bf((g * u) * (r2 * sg));
;           }
;         }
;       }
	v_pk_mul_f32 v[90:91], v[82:83], v[90:91]
	v_pk_mul_f32 v[82:83], v[82:83], v[132:133] op_sel_hi:[1,0]
	v_exp_f32_e32 v80, v80
	v_exp_f32_e32 v81, v81
	v_exp_f32_e32 v82, v82
	v_exp_f32_e32 v83, v83
	v_pk_add_f32 v[80:81], v[80:81], 1.0 op_sel_hi:[1,0]
	v_pk_add_f32 v[82:83], v[82:83], 1.0 op_sel_hi:[1,0]
	v_rcp_f32_e32 v80, v80
	v_rcp_f32_e32 v81, v81
	v_rcp_f32_e32 v82, v82
	v_rcp_f32_e32 v83, v83
	v_pk_mul_f32 v[80:81], v[80:81], v[134:135] op_sel_hi:[1,0]
	v_pk_mul_f32 v[82:83], v[82:83], v[134:135] op_sel_hi:[1,0]
	v_pk_mul_f32 v[88:89], v[88:89], v[80:81]
	v_pk_mul_f32 v[90:91], v[90:91], v[82:83]
	v_cvt_pk_bf16_f32 v86, v88, v89
	v_cvt_pk_bf16_f32 v87, v90, v91
	s_nop 1
	v_permlane16_swap_b32_e32 v84, v86
	v_permlane16_swap_b32_e32 v85, v87
	global_store_dwordx4 v133, v[84:87], s[10:11]
	v_add_u32_e32 v133, 0x81000, v135
	v_mul_f32_e32 v132, 0xbfb8aa3b, v153
	v_mul_f32_e32 v134, v153, v153
	ds_read_b32 v153, v149 offset:704
	v_pk_mul_f32 v[76:77], v[68:69], v[76:77]
	v_pk_mul_f32 v[68:69], v[68:69], v[132:133] op_sel_hi:[1,0]
	v_pk_mul_f32 v[78:79], v[70:71], v[78:79]
	v_pk_mul_f32 v[70:71], v[70:71], v[132:133] op_sel_hi:[1,0]
	v_exp_f32_e32 v68, v68
	v_exp_f32_e32 v69, v69
	v_exp_f32_e32 v70, v70
	v_exp_f32_e32 v71, v71
	v_pk_add_f32 v[68:69], v[68:69], 1.0 op_sel_hi:[1,0]
	v_pk_add_f32 v[70:71], v[70:71], 1.0 op_sel_hi:[1,0]
	v_rcp_f32_e32 v68, v68
	v_rcp_f32_e32 v69, v69
	v_rcp_f32_e32 v70, v70
	v_rcp_f32_e32 v71, v71
	v_pk_mul_f32 v[68:69], v[68:69], v[134:135] op_sel_hi:[1,0]
	v_pk_mul_f32 v[70:71], v[70:71], v[134:135] op_sel_hi:[1,0]
	v_pk_mul_f32 v[76:77], v[76:77], v[68:69]
	v_pk_mul_f32 v[78:79], v[78:79], v[70:71]
	v_cvt_pk_bf16_f32 v68, v76, v77
	v_cvt_pk_bf16_f32 v69, v78, v79
	v_pk_mul_f32 v[72:73], v[64:65], v[72:73]
	v_pk_mul_f32 v[64:65], v[64:65], v[132:133] op_sel_hi:[1,0]
	v_pk_mul_f32 v[74:75], v[66:67], v[74:75]
	v_pk_mul_f32 v[66:67], v[66:67], v[132:133] op_sel_hi:[1,0]
	v_exp_f32_e32 v64, v64
	v_exp_f32_e32 v65, v65
	v_exp_f32_e32 v66, v66
	v_exp_f32_e32 v67, v67
	v_pk_add_f32 v[64:65], v[64:65], 1.0 op_sel_hi:[1,0]
	v_pk_add_f32 v[66:67], v[66:67], 1.0 op_sel_hi:[1,0]
	v_rcp_f32_e32 v64, v64
	v_rcp_f32_e32 v65, v65
	v_rcp_f32_e32 v66, v66
	v_rcp_f32_e32 v67, v67
	v_pk_mul_f32 v[64:65], v[64:65], v[134:135] op_sel_hi:[1,0]
	v_pk_mul_f32 v[66:67], v[66:67], v[134:135] op_sel_hi:[1,0]
	v_pk_mul_f32 v[72:73], v[72:73], v[64:65]
	v_pk_mul_f32 v[74:75], v[74:75], v[66:67]
	v_cvt_pk_bf16_f32 v70, v72, v73
	v_cvt_pk_bf16_f32 v71, v74, v75
	s_nop 1
	v_permlane16_swap_b32_e32 v68, v70
	v_permlane16_swap_b32_e32 v69, v71
	global_store_dwordx4 v133, v[68:71], s[10:11]
	s_waitcnt lgkmcnt(0)
	v_add_u32_e32 v133, 0x158000, v135
	v_mul_f32_e32 v132, 0xbfb8aa3b, v150
	v_mul_f32_e32 v134, v150, v150
	v_pk_mul_f32 v[60:61], v[52:53], v[60:61]
	v_pk_mul_f32 v[52:53], v[52:53], v[132:133] op_sel_hi:[1,0]
	v_pk_mul_f32 v[62:63], v[54:55], v[62:63]
	v_pk_mul_f32 v[54:55], v[54:55], v[132:133] op_sel_hi:[1,0]
	v_exp_f32_e32 v52, v52
	v_exp_f32_e32 v53, v53
	v_exp_f32_e32 v54, v54
	v_exp_f32_e32 v55, v55
	v_pk_add_f32 v[52:53], v[52:53], 1.0 op_sel_hi:[1,0]
	v_pk_add_f32 v[54:55], v[54:55], 1.0 op_sel_hi:[1,0]
	v_rcp_f32_e32 v52, v52
	v_rcp_f32_e32 v53, v53
	v_rcp_f32_e32 v54, v54
	v_rcp_f32_e32 v55, v55
	v_pk_mul_f32 v[52:53], v[52:53], v[134:135] op_sel_hi:[1,0]
	v_pk_mul_f32 v[54:55], v[54:55], v[134:135] op_sel_hi:[1,0]
	v_pk_mul_f32 v[60:61], v[60:61], v[52:53]
	v_pk_mul_f32 v[62:63], v[62:63], v[54:55]
	v_cvt_pk_bf16_f32 v52, v60, v61
	v_cvt_pk_bf16_f32 v53, v62, v63
	v_pk_mul_f32 v[56:57], v[48:49], v[56:57]
	v_pk_mul_f32 v[48:49], v[48:49], v[132:133] op_sel_hi:[1,0]
	v_pk_mul_f32 v[58:59], v[50:51], v[58:59]
	v_pk_mul_f32 v[50:51], v[50:51], v[132:133] op_sel_hi:[1,0]
	v_exp_f32_e32 v48, v48
	v_exp_f32_e32 v49, v49
	v_exp_f32_e32 v50, v50
	v_exp_f32_e32 v51, v51
	v_pk_add_f32 v[48:49], v[48:49], 1.0 op_sel_hi:[1,0]
	v_pk_add_f32 v[50:51], v[50:51], 1.0 op_sel_hi:[1,0]
	v_rcp_f32_e32 v48, v48
	v_rcp_f32_e32 v49, v49
	v_rcp_f32_e32 v50, v50
	v_rcp_f32_e32 v51, v51
	v_pk_mul_f32 v[48:49], v[48:49], v[134:135] op_sel_hi:[1,0]
	v_pk_mul_f32 v[50:51], v[50:51], v[134:135] op_sel_hi:[1,0]
	v_pk_mul_f32 v[56:57], v[56:57], v[48:49]
	v_pk_mul_f32 v[58:59], v[58:59], v[50:51]
	v_cvt_pk_bf16_f32 v54, v56, v57
	v_cvt_pk_bf16_f32 v55, v58, v59
	s_nop 1
	v_permlane16_swap_b32_e32 v52, v54
	v_permlane16_swap_b32_e32 v53, v55
	global_store_dwordx4 v133, v[52:55], s[10:11]
	v_add_u32_e32 v133, 0x183000, v135
	v_mul_f32_e32 v132, 0xbfb8aa3b, v151
	v_mul_f32_e32 v134, v151, v151
	v_pk_mul_f32 v[44:45], v[36:37], v[44:45]
	v_pk_mul_f32 v[36:37], v[36:37], v[132:133] op_sel_hi:[1,0]
	v_pk_mul_f32 v[46:47], v[38:39], v[46:47]
	v_pk_mul_f32 v[38:39], v[38:39], v[132:133] op_sel_hi:[1,0]
	v_exp_f32_e32 v36, v36
	v_exp_f32_e32 v37, v37
	v_exp_f32_e32 v38, v38
	v_exp_f32_e32 v39, v39
	v_pk_add_f32 v[36:37], v[36:37], 1.0 op_sel_hi:[1,0]
	v_pk_add_f32 v[38:39], v[38:39], 1.0 op_sel_hi:[1,0]
	v_rcp_f32_e32 v36, v36
	v_rcp_f32_e32 v37, v37
	v_rcp_f32_e32 v38, v38
	v_rcp_f32_e32 v39, v39
	v_pk_mul_f32 v[36:37], v[36:37], v[134:135] op_sel_hi:[1,0]
	v_pk_mul_f32 v[38:39], v[38:39], v[134:135] op_sel_hi:[1,0]
; __device__ __forceinline__ u16 f2bf(float x) { return (u16)(cvtpk(x, x) & 0xffffu); }
; #define UNR _Pragma("unroll")
; #define WAIT_V(n) asm volatile("s_waitcnt vmcnt(" #n ")" ::: "memory")
; template <int EPI, int lda, int ldb, int N, int K>
; __device__ __forceinline__ void gemm_phase(const u16* __restrict__ A, const u16* __restrict__ Bt, const GemmEpi ep, int wv) {
;     ...
;       UNR for (int ai = 0; ai < 2; ++ai) UNR for (int m = 0; m < 4; ++m) {
;         const int rl0 = ai * HALF + wr * 64 + m * 16 + fq * 4;
;         const f32x4 r4 = *reinterpret_cast<const f32x4*>(lrs + rl0);
;         UNR for (int j = 0; j < 4; ++j) {
;           const int row = brow + rl0 + j;
;           const float rs = r4[j], ce = -1.4426950408889634f * rs, r2 = rs * rs;
;           UNR for (int n = 0; n < 2; ++n) {
;             const int col = (bcol >> 1) + wc * 32 + n * 16 + fr;
;             const float g = acc[ai][0][m][n][j], u = acc[ai][1][m][n][j];
;             const float sg = __builtin_amdgcn_rcpf(1.f + __builtin_amdgcn_exp2f(ce * g));
;             out[(size_t)row * ep.ldc + col] = f2bf((g * u) * (r2 * sg));
;           }
;         }
;       }
;     ...
;     if constexpr (PF) {
;       WAIT_V(0);
;       __syncthreads();
;       if constexpr (CONS) { if (more && tidx < 256) { float sq = 0.f; UNR for (int pp = 0; pp < 8; ++pp) sq += nss[pp];
;         lrs[tidx] = rsqrtf(sq * (1.f / DM) + 1e-6f); } }
;       if (!more) break;
	v_pk_mul_f32 v[44:45], v[44:45], v[36:37]
	v_pk_mul_f32 v[46:47], v[46:47], v[38:39]
	v_cvt_pk_bf16_f32 v36, v44, v45
	v_cvt_pk_bf16_f32 v37, v46, v47
	v_pk_mul_f32 v[40:41], v[32:33], v[40:41]
	v_pk_mul_f32 v[32:33], v[32:33], v[132:133] op_sel_hi:[1,0]
	v_pk_mul_f32 v[42:43], v[34:35], v[42:43]
	v_pk_mul_f32 v[34:35], v[34:35], v[132:133] op_sel_hi:[1,0]
	v_exp_f32_e32 v32, v32
	v_exp_f32_e32 v33, v33
	v_exp_f32_e32 v34, v34
	v_exp_f32_e32 v35, v35
	v_pk_add_f32 v[32:33], v[32:33], 1.0 op_sel_hi:[1,0]
	v_pk_add_f32 v[34:35], v[34:35], 1.0 op_sel_hi:[1,0]
	v_rcp_f32_e32 v32, v32
	v_rcp_f32_e32 v33, v33
	v_rcp_f32_e32 v34, v34
	v_rcp_f32_e32 v35, v35
	v_pk_mul_f32 v[32:33], v[32:33], v[134:135] op_sel_hi:[1,0]
	v_pk_mul_f32 v[34:35], v[34:35], v[134:135] op_sel_hi:[1,0]
	v_pk_mul_f32 v[40:41], v[40:41], v[32:33]
	v_pk_mul_f32 v[42:43], v[42:43], v[34:35]
	v_cvt_pk_bf16_f32 v38, v40, v41
	v_cvt_pk_bf16_f32 v39, v42, v43
	s_nop 1
	v_permlane16_swap_b32_e32 v36, v38
	v_permlane16_swap_b32_e32 v37, v39
	global_store_dwordx4 v133, v[36:39], s[10:11]
	v_add_u32_e32 v133, 0x1ae000, v135
	v_mul_f32_e32 v132, 0xbfb8aa3b, v152
	v_mul_f32_e32 v134, v152, v152
	v_pk_mul_f32 v[28:29], v[20:21], v[28:29]
	v_pk_mul_f32 v[20:21], v[20:21], v[132:133] op_sel_hi:[1,0]
	v_pk_mul_f32 v[30:31], v[22:23], v[30:31]
	v_pk_mul_f32 v[22:23], v[22:23], v[132:133] op_sel_hi:[1,0]
	v_exp_f32_e32 v20, v20
	v_exp_f32_e32 v21, v21
	v_exp_f32_e32 v22, v22
	v_exp_f32_e32 v23, v23
	v_pk_add_f32 v[20:21], v[20:21], 1.0 op_sel_hi:[1,0]
	v_pk_add_f32 v[22:23], v[22:23], 1.0 op_sel_hi:[1,0]
	v_rcp_f32_e32 v20, v20
	v_rcp_f32_e32 v21, v21
	v_rcp_f32_e32 v22, v22
	v_rcp_f32_e32 v23, v23
	v_pk_mul_f32 v[20:21], v[20:21], v[134:135] op_sel_hi:[1,0]
	v_pk_mul_f32 v[22:23], v[22:23], v[134:135] op_sel_hi:[1,0]
	v_pk_mul_f32 v[28:29], v[28:29], v[20:21]
	v_pk_mul_f32 v[30:31], v[30:31], v[22:23]
	v_cvt_pk_bf16_f32 v20, v28, v29
	v_cvt_pk_bf16_f32 v21, v30, v31
	v_pk_mul_f32 v[24:25], v[16:17], v[24:25]
	v_pk_mul_f32 v[16:17], v[16:17], v[132:133] op_sel_hi:[1,0]
	v_pk_mul_f32 v[26:27], v[18:19], v[26:27]
	v_pk_mul_f32 v[18:19], v[18:19], v[132:133] op_sel_hi:[1,0]
	v_exp_f32_e32 v16, v16
	v_exp_f32_e32 v17, v17
	v_exp_f32_e32 v18, v18
	v_exp_f32_e32 v19, v19
	v_pk_add_f32 v[16:17], v[16:17], 1.0 op_sel_hi:[1,0]
	v_pk_add_f32 v[18:19], v[18:19], 1.0 op_sel_hi:[1,0]
	v_rcp_f32_e32 v16, v16
	v_rcp_f32_e32 v17, v17
	v_rcp_f32_e32 v18, v18
	v_rcp_f32_e32 v19, v19
	v_pk_mul_f32 v[16:17], v[16:17], v[134:135] op_sel_hi:[1,0]
	v_pk_mul_f32 v[18:19], v[18:19], v[134:135] op_sel_hi:[1,0]
	v_pk_mul_f32 v[24:25], v[24:25], v[16:17]
	v_pk_mul_f32 v[26:27], v[26:27], v[18:19]
	v_cvt_pk_bf16_f32 v22, v24, v25
	v_cvt_pk_bf16_f32 v23, v26, v27
	s_nop 1
	v_permlane16_swap_b32_e32 v20, v22
	v_permlane16_swap_b32_e32 v21, v23
	global_store_dwordx4 v133, v[20:23], s[10:11]
	v_add_u32_e32 v133, 0x1d9000, v135
	v_mul_f32_e32 v132, 0xbfb8aa3b, v153
	v_mul_f32_e32 v134, v153, v153
	v_pk_mul_f32 v[12:13], v[4:5], v[12:13]
	v_pk_mul_f32 v[4:5], v[4:5], v[132:133] op_sel_hi:[1,0]
	v_pk_mul_f32 v[14:15], v[6:7], v[14:15]
	v_pk_mul_f32 v[6:7], v[6:7], v[132:133] op_sel_hi:[1,0]
	v_exp_f32_e32 v4, v4
	v_exp_f32_e32 v5, v5
	v_exp_f32_e32 v6, v6
	v_exp_f32_e32 v7, v7
	v_pk_add_f32 v[4:5], v[4:5], 1.0 op_sel_hi:[1,0]
	v_pk_add_f32 v[6:7], v[6:7], 1.0 op_sel_hi:[1,0]
	v_rcp_f32_e32 v4, v4
	v_rcp_f32_e32 v5, v5
	v_rcp_f32_e32 v6, v6
	v_rcp_f32_e32 v7, v7
	v_pk_mul_f32 v[4:5], v[4:5], v[134:135] op_sel_hi:[1,0]
	v_pk_mul_f32 v[6:7], v[6:7], v[134:135] op_sel_hi:[1,0]
	v_pk_mul_f32 v[12:13], v[12:13], v[4:5]
	v_pk_mul_f32 v[14:15], v[14:15], v[6:7]
	v_cvt_pk_bf16_f32 v4, v12, v13
	v_cvt_pk_bf16_f32 v5, v14, v15
	v_pk_mul_f32 v[8:9], v[0:1], v[8:9]
	v_pk_mul_f32 v[0:1], v[0:1], v[132:133] op_sel_hi:[1,0]
	v_pk_mul_f32 v[10:11], v[2:3], v[10:11]
	v_pk_mul_f32 v[2:3], v[2:3], v[132:133] op_sel_hi:[1,0]
	v_exp_f32_e32 v0, v0
	v_exp_f32_e32 v1, v1
	v_exp_f32_e32 v2, v2
	v_exp_f32_e32 v3, v3
	v_pk_add_f32 v[0:1], v[0:1], 1.0 op_sel_hi:[1,0]
	v_pk_add_f32 v[2:3], v[2:3], 1.0 op_sel_hi:[1,0]
	v_rcp_f32_e32 v0, v0
	v_rcp_f32_e32 v1, v1
	v_rcp_f32_e32 v2, v2
	v_rcp_f32_e32 v3, v3
	v_pk_mul_f32 v[0:1], v[0:1], v[134:135] op_sel_hi:[1,0]
	v_pk_mul_f32 v[2:3], v[2:3], v[134:135] op_sel_hi:[1,0]
	v_pk_mul_f32 v[8:9], v[8:9], v[0:1]
	v_pk_mul_f32 v[10:11], v[10:11], v[2:3]
	v_cvt_pk_bf16_f32 v6, v8, v9
	v_cvt_pk_bf16_f32 v7, v10, v11
	s_nop 1
	v_permlane16_swap_b32_e32 v4, v6
	v_permlane16_swap_b32_e32 v5, v7
	global_store_dwordx4 v133, v[4:7], s[10:11]
	s_waitcnt vmcnt(8)
	s_waitcnt vmcnt(8)
	v_add_f32_e32 v148, 0, v131
	s_barrier
	s_and_saveexec_b64 s[38:39], s[46:47]
	s_cbranch_execz .LBB0_49
	v_add_f32_e32 v0, v141, v148
	v_add_f32_e32 v0, v140, v0
	v_add_f32_e32 v0, v139, v0
	v_add_f32_e32 v0, v138, v0
	v_add_f32_e32 v0, v137, v0
	v_add_f32_e32 v0, v136, v0
	v_add_f32_e32 v0, v128, v0
	v_fmamk_f32 v0, v0, 0x3a000000, v143
	v_mul_f32_e32 v1, 0x4b800000, v0
	v_cmp_gt_f32_e32 vcc, s64, v0
	s_nop 1
	v_cndmask_b32_e32 v0, v0, v1, vcc
	v_rsq_f32_e32 v0, v0
	v_lshl_add_u32 v1, v130, 2, 0
	v_add_u32_e32 v1, 0x20000, v1
	v_mul_f32_e32 v2, 0x45800000, v0
	v_cndmask_b32_e32 v0, v0, v2, vcc
	ds_write_b32 v1, v0
	s_branch .LBB0_49

; __device__ __forceinline__ u16 f2bf(float x) { return (u16)(cvtpk(x, x) & 0xffffu); }
; #define UNR _Pragma("unroll")
; template <int EPI, int lda, int ldb, int N, int K>
; __device__ __forceinline__ void gemm_phase(const u16* __restrict__ A, const u16* __restrict__ Bt, const GemmEpi ep, int wv) {
;     ...
;     if constexpr (EPI == EPI_SWIGLU) {
;       u16* out = reinterpret_cast<u16*>(ep.out0);
;       UNR for (int ai = 0; ai < 2; ++ai) UNR for (int m = 0; m < 4; ++m) {
;         const int rl0 = ai * HALF + wr * 64 + m * 16 + fq * 4;
;         const f32x4 r4 = *reinterpret_cast<const f32x4*>(lrs + rl0);
;         UNR for (int j = 0; j < 4; ++j) {
;           const int row = brow + rl0 + j;
;           const float rs = r4[j], ce = -1.4426950408889634f * rs, r2 = rs * rs;
;           UNR for (int n = 0; n < 2; ++n) {
;             const int col = (bcol >> 1) + wc * 32 + n * 16 + fr;
;             const float g = acc[ai][0][m][n][j], u = acc[ai][1][m][n][j];
;             const float sg = __builtin_amdgcn_rcpf(1.f + __builtin_amdgcn_exp2f(ce * g));
;             out[(size_t)row * ep.ldc + col] = f2bf((g * u) * (r2 * sg));
;           }
;         }
;       }
.LBB0_777:
	s_or_b64 exec, exec, s[56:57]
	v_and_b32_e32 v132, 15, v130
	v_lshrrev_b32_e32 v134, 8, v130
	v_lshl_add_u32 v132, v134, 6, v132
	v_lshlrev_b32_e32 v149, 2, v132
	v_add_u32_e32 v149, 0x20000, v149
	ds_read_b32 v150, v149 offset:0
	ds_read_b32 v151, v149 offset:64
	ds_read_b32 v152, v149 offset:128
	ds_read_b32 v153, v149 offset:192
	v_add_u32_e32 v132, s48, v132
	v_mul_u32_u24_e32 v135, 0x2b00, v132
	v_bfe_u32 v134, v130, 6, 2
	v_lshlrev_b32_e32 v134, 5, v134
	v_bfe_u32 v132, v130, 4, 1
	v_lshl_add_u32 v134, v132, 4, v134
	v_bfe_u32 v132, v130, 5, 1
	v_lshl_add_u32 v134, v132, 3, v134
	v_lshrrev_b32_e64 v132, 1, s49
	v_add_u32_e32 v134, v132, v134
	v_lshl_add_u32 v135, v134, 1, v135
	s_waitcnt lgkmcnt(0)
	v_mul_f32_e32 v132, 0xbfb8aa3b, v150
	v_mul_f32_e32 v134, v150, v150
	ds_read_b32 v150, v149 offset:512
	v_pk_mul_f32 v[124:125], v[116:117], v[124:125]
	v_pk_mul_f32 v[116:117], v[116:117], v[132:133] op_sel_hi:[1,0]
	v_pk_mul_f32 v[126:127], v[118:119], v[126:127]
	v_pk_mul_f32 v[118:119], v[118:119], v[132:133] op_sel_hi:[1,0]
	v_exp_f32_e32 v116, v116
	v_exp_f32_e32 v117, v117
	v_exp_f32_e32 v118, v118
	v_exp_f32_e32 v119, v119
	v_pk_add_f32 v[116:117], v[116:117], 1.0 op_sel_hi:[1,0]
	v_pk_add_f32 v[118:119], v[118:119], 1.0 op_sel_hi:[1,0]
	v_rcp_f32_e32 v116, v116
	v_rcp_f32_e32 v117, v117
	v_rcp_f32_e32 v118, v118
	v_rcp_f32_e32 v119, v119
	v_pk_mul_f32 v[116:117], v[116:117], v[134:135] op_sel_hi:[1,0]
	v_pk_mul_f32 v[118:119], v[118:119], v[134:135] op_sel_hi:[1,0]
	v_pk_mul_f32 v[124:125], v[124:125], v[116:117]
	v_pk_mul_f32 v[126:127], v[126:127], v[118:119]
	v_cvt_pk_bf16_f32 v116, v124, v125
	v_cvt_pk_bf16_f32 v117, v126, v127
	v_pk_mul_f32 v[120:121], v[112:113], v[120:121]
	v_pk_mul_f32 v[112:113], v[112:113], v[132:133] op_sel_hi:[1,0]
	v_pk_mul_f32 v[122:123], v[114:115], v[122:123]
	v_pk_mul_f32 v[114:115], v[114:115], v[132:133] op_sel_hi:[1,0]
	v_exp_f32_e32 v112, v112
	v_exp_f32_e32 v113, v113
	v_exp_f32_e32 v114, v114
	v_exp_f32_e32 v115, v115
	v_pk_add_f32 v[112:113], v[112:113], 1.0 op_sel_hi:[1,0]
	v_pk_add_f32 v[114:115], v[114:115], 1.0 op_sel_hi:[1,0]
	v_rcp_f32_e32 v112, v112
	v_rcp_f32_e32 v113, v113
	v_rcp_f32_e32 v114, v114
	v_rcp_f32_e32 v115, v115
	v_pk_mul_f32 v[112:113], v[112:113], v[134:135] op_sel_hi:[1,0]
	v_pk_mul_f32 v[114:115], v[114:115], v[134:135] op_sel_hi:[1,0]
	v_pk_mul_f32 v[120:121], v[120:121], v[112:113]
	v_pk_mul_f32 v[122:123], v[122:123], v[114:115]
	v_cvt_pk_bf16_f32 v118, v120, v121
	v_cvt_pk_bf16_f32 v119, v122, v123
	s_nop 1
	v_permlane16_swap_b32_e32 v116, v118
	v_permlane16_swap_b32_e32 v117, v119
	global_store_dwordx4 v135, v[116:119], s[14:15]
	v_add_u32_e32 v133, 0x2b000, v135
	v_mul_f32_e32 v132, 0xbfb8aa3b, v151
	v_mul_f32_e32 v134, v151, v151
	ds_read_b32 v151, v149 offset:576
	v_pk_mul_f32 v[108:109], v[100:101], v[108:109]
	v_pk_mul_f32 v[100:101], v[100:101], v[132:133] op_sel_hi:[1,0]
	v_pk_mul_f32 v[110:111], v[102:103], v[110:111]
	v_pk_mul_f32 v[102:103], v[102:103], v[132:133] op_sel_hi:[1,0]
	v_exp_f32_e32 v100, v100
	v_exp_f32_e32 v101, v101
	v_exp_f32_e32 v102, v102
	v_exp_f32_e32 v103, v103
	v_pk_add_f32 v[100:101], v[100:101], 1.0 op_sel_hi:[1,0]
	v_pk_add_f32 v[102:103], v[102:103], 1.0 op_sel_hi:[1,0]
	v_rcp_f32_e32 v100, v100
	v_rcp_f32_e32 v101, v101
	v_rcp_f32_e32 v102, v102
	v_rcp_f32_e32 v103, v103
	v_pk_mul_f32 v[100:101], v[100:101], v[134:135] op_sel_hi:[1,0]
	v_pk_mul_f32 v[102:103], v[102:103], v[134:135] op_sel_hi:[1,0]
	v_pk_mul_f32 v[108:109], v[108:109], v[100:101]
	v_pk_mul_f32 v[110:111], v[110:111], v[102:103]
	v_cvt_pk_bf16_f32 v100, v108, v109
	v_cvt_pk_bf16_f32 v101, v110, v111
	v_pk_mul_f32 v[104:105], v[96:97], v[104:105]
	v_pk_mul_f32 v[96:97], v[96:97], v[132:133] op_sel_hi:[1,0]
	v_pk_mul_f32 v[106:107], v[98:99], v[106:107]
	v_pk_mul_f32 v[98:99], v[98:99], v[132:133] op_sel_hi:[1,0]
	v_exp_f32_e32 v96, v96
	v_exp_f32_e32 v97, v97
	v_exp_f32_e32 v98, v98
	v_exp_f32_e32 v99, v99
	v_pk_add_f32 v[96:97], v[96:97], 1.0 op_sel_hi:[1,0]
	v_pk_add_f32 v[98:99], v[98:99], 1.0 op_sel_hi:[1,0]
	v_rcp_f32_e32 v96, v96
	v_rcp_f32_e32 v97, v97
	v_rcp_f32_e32 v98, v98
	v_rcp_f32_e32 v99, v99
	v_pk_mul_f32 v[96:97], v[96:97], v[134:135] op_sel_hi:[1,0]
	v_pk_mul_f32 v[98:99], v[98:99], v[134:135] op_sel_hi:[1,0]
	v_pk_mul_f32 v[104:105], v[104:105], v[96:97]
	v_pk_mul_f32 v[106:107], v[106:107], v[98:99]
	v_cvt_pk_bf16_f32 v102, v104, v105
	v_cvt_pk_bf16_f32 v103, v106, v107
	s_nop 1
	v_permlane16_swap_b32_e32 v100, v102
	v_permlane16_swap_b32_e32 v101, v103
	global_store_dwordx4 v133, v[100:103], s[14:15]
	v_add_u32_e32 v133, 0x56000, v135
	v_mul_f32_e32 v132, 0xbfb8aa3b, v152
	v_mul_f32_e32 v134, v152, v152
	ds_read_b32 v152, v149 offset:640
	v_pk_mul_f32 v[92:93], v[84:85], v[92:93]
	v_pk_mul_f32 v[84:85], v[84:85], v[132:133] op_sel_hi:[1,0]
	v_pk_mul_f32 v[94:95], v[86:87], v[94:95]
	v_pk_mul_f32 v[86:87], v[86:87], v[132:133] op_sel_hi:[1,0]
	v_exp_f32_e32 v84, v84
	v_exp_f32_e32 v85, v85
	v_exp_f32_e32 v86, v86
	v_exp_f32_e32 v87, v87
	v_pk_add_f32 v[84:85], v[84:85], 1.0 op_sel_hi:[1,0]
	v_pk_add_f32 v[86:87], v[86:87], 1.0 op_sel_hi:[1,0]
	v_rcp_f32_e32 v84, v84
	v_rcp_f32_e32 v85, v85
	v_rcp_f32_e32 v86, v86
	v_rcp_f32_e32 v87, v87
	v_pk_mul_f32 v[84:85], v[84:85], v[134:135] op_sel_hi:[1,0]
	v_pk_mul_f32 v[86:87], v[86:87], v[134:135] op_sel_hi:[1,0]
	v_pk_mul_f32 v[92:93], v[92:93], v[84:85]
	v_pk_mul_f32 v[94:95], v[94:95], v[86:87]
	v_cvt_pk_bf16_f32 v84, v92, v93
	v_cvt_pk_bf16_f32 v85, v94, v95
	v_pk_mul_f32 v[88:89], v[80:81], v[88:89]
	v_pk_mul_f32 v[80:81], v[80:81], v[132:133] op_sel_hi:[1,0]
; __device__ __forceinline__ u16 f2bf(float x) { return (u16)(cvtpk(x, x) & 0xffffu); }
; #define UNR _Pragma("unroll")
; template <int EPI, int lda, int ldb, int N, int K>
; __device__ __forceinline__ void gemm_phase(const u16* __restrict__ A, const u16* __restrict__ Bt, const GemmEpi ep, int wv) {
;     ...
;       UNR for (int ai = 0; ai < 2; ++ai) UNR for (int m = 0; m < 4; ++m) {
;         const int rl0 = ai * HALF + wr * 64 + m * 16 + fq * 4;
;         const f32x4 r4 = *reinterpret_cast<const f32x4*>(lrs + rl0);
;         UNR for (int j = 0; j < 4; ++j) {
;           const int row = brow + rl0 + j;
;           const float rs = r4[j], ce = -1.4426950408889634f * rs, r2 = rs * rs;
;           UNR for (int n = 0; n < 2; ++n) {
;             const int col = (bcol >> 1) + wc * 32 + n * 16 + fr;
;             const float g = acc[ai][0][m][n][j], u = acc[ai][1][m][n][j];
;             const float sg = __builtin_amdgcn_rcpf(1.f + __builtin_amdgcn_exp2f(ce * g));
;             out[(size_t)row * ep.ldc + col] = f2bf((g * u) * (r2 * sg));
;           }
;         }
;       }
	v_pk_mul_f32 v[90:91], v[82:83], v[90:91]
	v_pk_mul_f32 v[82:83], v[82:83], v[132:133] op_sel_hi:[1,0]
	v_exp_f32_e32 v80, v80
	v_exp_f32_e32 v81, v81
	v_exp_f32_e32 v82, v82
	v_exp_f32_e32 v83, v83
	v_pk_add_f32 v[80:81], v[80:81], 1.0 op_sel_hi:[1,0]
	v_pk_add_f32 v[82:83], v[82:83], 1.0 op_sel_hi:[1,0]
	v_rcp_f32_e32 v80, v80
	v_rcp_f32_e32 v81, v81
	v_rcp_f32_e32 v82, v82
	v_rcp_f32_e32 v83, v83
	v_pk_mul_f32 v[80:81], v[80:81], v[134:135] op_sel_hi:[1,0]
	v_pk_mul_f32 v[82:83], v[82:83], v[134:135] op_sel_hi:[1,0]
	v_pk_mul_f32 v[88:89], v[88:89], v[80:81]
	v_pk_mul_f32 v[90:91], v[90:91], v[82:83]
	v_cvt_pk_bf16_f32 v86, v88, v89
	v_cvt_pk_bf16_f32 v87, v90, v91
	s_nop 1
	v_permlane16_swap_b32_e32 v84, v86
	v_permlane16_swap_b32_e32 v85, v87
	global_store_dwordx4 v133, v[84:87], s[14:15]
	v_add_u32_e32 v133, 0x81000, v135
	v_mul_f32_e32 v132, 0xbfb8aa3b, v153
	v_mul_f32_e32 v134, v153, v153
	ds_read_b32 v153, v149 offset:704
	v_pk_mul_f32 v[76:77], v[68:69], v[76:77]
	v_pk_mul_f32 v[68:69], v[68:69], v[132:133] op_sel_hi:[1,0]
	v_pk_mul_f32 v[78:79], v[70:71], v[78:79]
	v_pk_mul_f32 v[70:71], v[70:71], v[132:133] op_sel_hi:[1,0]
	v_exp_f32_e32 v68, v68
	v_exp_f32_e32 v69, v69
	v_exp_f32_e32 v70, v70
	v_exp_f32_e32 v71, v71
	v_pk_add_f32 v[68:69], v[68:69], 1.0 op_sel_hi:[1,0]
	v_pk_add_f32 v[70:71], v[70:71], 1.0 op_sel_hi:[1,0]
	v_rcp_f32_e32 v68, v68
	v_rcp_f32_e32 v69, v69
	v_rcp_f32_e32 v70, v70
	v_rcp_f32_e32 v71, v71
	v_pk_mul_f32 v[68:69], v[68:69], v[134:135] op_sel_hi:[1,0]
	v_pk_mul_f32 v[70:71], v[70:71], v[134:135] op_sel_hi:[1,0]
	v_pk_mul_f32 v[76:77], v[76:77], v[68:69]
	v_pk_mul_f32 v[78:79], v[78:79], v[70:71]
	v_cvt_pk_bf16_f32 v68, v76, v77
	v_cvt_pk_bf16_f32 v69, v78, v79
	v_pk_mul_f32 v[72:73], v[64:65], v[72:73]
	v_pk_mul_f32 v[64:65], v[64:65], v[132:133] op_sel_hi:[1,0]
	v_pk_mul_f32 v[74:75], v[66:67], v[74:75]
	v_pk_mul_f32 v[66:67], v[66:67], v[132:133] op_sel_hi:[1,0]
	v_exp_f32_e32 v64, v64
	v_exp_f32_e32 v65, v65
	v_exp_f32_e32 v66, v66
	v_exp_f32_e32 v67, v67
	v_pk_add_f32 v[64:65], v[64:65], 1.0 op_sel_hi:[1,0]
	v_pk_add_f32 v[66:67], v[66:67], 1.0 op_sel_hi:[1,0]
	v_rcp_f32_e32 v64, v64
	v_rcp_f32_e32 v65, v65
	v_rcp_f32_e32 v66, v66
	v_rcp_f32_e32 v67, v67
	v_pk_mul_f32 v[64:65], v[64:65], v[134:135] op_sel_hi:[1,0]
	v_pk_mul_f32 v[66:67], v[66:67], v[134:135] op_sel_hi:[1,0]
	v_pk_mul_f32 v[72:73], v[72:73], v[64:65]
	v_pk_mul_f32 v[74:75], v[74:75], v[66:67]
	v_cvt_pk_bf16_f32 v70, v72, v73
	v_cvt_pk_bf16_f32 v71, v74, v75
	s_nop 1
	v_permlane16_swap_b32_e32 v68, v70
	v_permlane16_swap_b32_e32 v69, v71
	global_store_dwordx4 v133, v[68:71], s[14:15]
	s_waitcnt lgkmcnt(0)
	v_add_u32_e32 v133, 0x158000, v135
	v_mul_f32_e32 v132, 0xbfb8aa3b, v150
	v_mul_f32_e32 v134, v150, v150
	v_pk_mul_f32 v[60:61], v[52:53], v[60:61]
	v_pk_mul_f32 v[52:53], v[52:53], v[132:133] op_sel_hi:[1,0]
	v_pk_mul_f32 v[62:63], v[54:55], v[62:63]
	v_pk_mul_f32 v[54:55], v[54:55], v[132:133] op_sel_hi:[1,0]
	v_exp_f32_e32 v52, v52
	v_exp_f32_e32 v53, v53
	v_exp_f32_e32 v54, v54
	v_exp_f32_e32 v55, v55
	v_pk_add_f32 v[52:53], v[52:53], 1.0 op_sel_hi:[1,0]
	v_pk_add_f32 v[54:55], v[54:55], 1.0 op_sel_hi:[1,0]
	v_rcp_f32_e32 v52, v52
	v_rcp_f32_e32 v53, v53
	v_rcp_f32_e32 v54, v54
	v_rcp_f32_e32 v55, v55
	v_pk_mul_f32 v[52:53], v[52:53], v[134:135] op_sel_hi:[1,0]
	v_pk_mul_f32 v[54:55], v[54:55], v[134:135] op_sel_hi:[1,0]
	v_pk_mul_f32 v[60:61], v[60:61], v[52:53]
	v_pk_mul_f32 v[62:63], v[62:63], v[54:55]
	v_cvt_pk_bf16_f32 v52, v60, v61
	v_cvt_pk_bf16_f32 v53, v62, v63
	v_pk_mul_f32 v[56:57], v[48:49], v[56:57]
	v_pk_mul_f32 v[48:49], v[48:49], v[132:133] op_sel_hi:[1,0]
	v_pk_mul_f32 v[58:59], v[50:51], v[58:59]
	v_pk_mul_f32 v[50:51], v[50:51], v[132:133] op_sel_hi:[1,0]
	v_exp_f32_e32 v48, v48
	v_exp_f32_e32 v49, v49
	v_exp_f32_e32 v50, v50
	v_exp_f32_e32 v51, v51
	v_pk_add_f32 v[48:49], v[48:49], 1.0 op_sel_hi:[1,0]
	v_pk_add_f32 v[50:51], v[50:51], 1.0 op_sel_hi:[1,0]
	v_rcp_f32_e32 v48, v48
	v_rcp_f32_e32 v49, v49
	v_rcp_f32_e32 v50, v50
	v_rcp_f32_e32 v51, v51
	v_pk_mul_f32 v[48:49], v[48:49], v[134:135] op_sel_hi:[1,0]
	v_pk_mul_f32 v[50:51], v[50:51], v[134:135] op_sel_hi:[1,0]
	v_pk_mul_f32 v[56:57], v[56:57], v[48:49]
	v_pk_mul_f32 v[58:59], v[58:59], v[50:51]
	v_cvt_pk_bf16_f32 v54, v56, v57
	v_cvt_pk_bf16_f32 v55, v58, v59
	s_nop 1
	v_permlane16_swap_b32_e32 v52, v54
	v_permlane16_swap_b32_e32 v53, v55
	global_store_dwordx4 v133, v[52:55], s[14:15]
	v_add_u32_e32 v133, 0x183000, v135
	v_mul_f32_e32 v132, 0xbfb8aa3b, v151
	v_mul_f32_e32 v134, v151, v151
	v_pk_mul_f32 v[44:45], v[36:37], v[44:45]
	v_pk_mul_f32 v[36:37], v[36:37], v[132:133] op_sel_hi:[1,0]
	v_pk_mul_f32 v[46:47], v[38:39], v[46:47]
	v_pk_mul_f32 v[38:39], v[38:39], v[132:133] op_sel_hi:[1,0]
	v_exp_f32_e32 v36, v36
	v_exp_f32_e32 v37, v37
	v_exp_f32_e32 v38, v38
	v_exp_f32_e32 v39, v39
	v_pk_add_f32 v[36:37], v[36:37], 1.0 op_sel_hi:[1,0]
	v_pk_add_f32 v[38:39], v[38:39], 1.0 op_sel_hi:[1,0]
	v_rcp_f32_e32 v36, v36
	v_rcp_f32_e32 v37, v37
	v_rcp_f32_e32 v38, v38
	v_rcp_f32_e32 v39, v39
	v_pk_mul_f32 v[36:37], v[36:37], v[134:135] op_sel_hi:[1,0]
	v_pk_mul_f32 v[38:39], v[38:39], v[134:135] op_sel_hi:[1,0]
; __device__ __forceinline__ u16 f2bf(float x) { return (u16)(cvtpk(x, x) & 0xffffu); }
; #define UNR _Pragma("unroll")
; #define WAIT_V(n) asm volatile("s_waitcnt vmcnt(" #n ")" ::: "memory")
; template <int EPI, int lda, int ldb, int N, int K>
; __device__ __forceinline__ void gemm_phase(const u16* __restrict__ A, const u16* __restrict__ Bt, const GemmEpi ep, int wv) {
;     ...
;       UNR for (int ai = 0; ai < 2; ++ai) UNR for (int m = 0; m < 4; ++m) {
;         const int rl0 = ai * HALF + wr * 64 + m * 16 + fq * 4;
;         const f32x4 r4 = *reinterpret_cast<const f32x4*>(lrs + rl0);
;         UNR for (int j = 0; j < 4; ++j) {
;           const int row = brow + rl0 + j;
;           const float rs = r4[j], ce = -1.4426950408889634f * rs, r2 = rs * rs;
;           UNR for (int n = 0; n < 2; ++n) {
;             const int col = (bcol >> 1) + wc * 32 + n * 16 + fr;
;             const float g = acc[ai][0][m][n][j], u = acc[ai][1][m][n][j];
;             const float sg = __builtin_amdgcn_rcpf(1.f + __builtin_amdgcn_exp2f(ce * g));
;             out[(size_t)row * ep.ldc + col] = f2bf((g * u) * (r2 * sg));
;           }
;         }
;       }
;     ...
;     if constexpr (PF) {
;       WAIT_V(0);
;       __syncthreads();
;       if constexpr (CONS) { if (more && tidx < 256) { float sq = 0.f; UNR for (int pp = 0; pp < 8; ++pp) sq += nss[pp];
;         lrs[tidx] = rsqrtf(sq * (1.f / DM) + 1e-6f); } }
;       if (!more) break;
	v_pk_mul_f32 v[44:45], v[44:45], v[36:37]
	v_pk_mul_f32 v[46:47], v[46:47], v[38:39]
	v_cvt_pk_bf16_f32 v36, v44, v45
	v_cvt_pk_bf16_f32 v37, v46, v47
	v_pk_mul_f32 v[40:41], v[32:33], v[40:41]
	v_pk_mul_f32 v[32:33], v[32:33], v[132:133] op_sel_hi:[1,0]
	v_pk_mul_f32 v[42:43], v[34:35], v[42:43]
	v_pk_mul_f32 v[34:35], v[34:35], v[132:133] op_sel_hi:[1,0]
	v_exp_f32_e32 v32, v32
	v_exp_f32_e32 v33, v33
	v_exp_f32_e32 v34, v34
	v_exp_f32_e32 v35, v35
	v_pk_add_f32 v[32:33], v[32:33], 1.0 op_sel_hi:[1,0]
	v_pk_add_f32 v[34:35], v[34:35], 1.0 op_sel_hi:[1,0]
	v_rcp_f32_e32 v32, v32
	v_rcp_f32_e32 v33, v33
	v_rcp_f32_e32 v34, v34
	v_rcp_f32_e32 v35, v35
	v_pk_mul_f32 v[32:33], v[32:33], v[134:135] op_sel_hi:[1,0]
	v_pk_mul_f32 v[34:35], v[34:35], v[134:135] op_sel_hi:[1,0]
	v_pk_mul_f32 v[40:41], v[40:41], v[32:33]
	v_pk_mul_f32 v[42:43], v[42:43], v[34:35]
	v_cvt_pk_bf16_f32 v38, v40, v41
	v_cvt_pk_bf16_f32 v39, v42, v43
	s_nop 1
	v_permlane16_swap_b32_e32 v36, v38
	v_permlane16_swap_b32_e32 v37, v39
	global_store_dwordx4 v133, v[36:39], s[14:15]
	v_add_u32_e32 v133, 0x1ae000, v135
	v_mul_f32_e32 v132, 0xbfb8aa3b, v152
	v_mul_f32_e32 v134, v152, v152
	v_pk_mul_f32 v[28:29], v[20:21], v[28:29]
	v_pk_mul_f32 v[20:21], v[20:21], v[132:133] op_sel_hi:[1,0]
	v_pk_mul_f32 v[30:31], v[22:23], v[30:31]
	v_pk_mul_f32 v[22:23], v[22:23], v[132:133] op_sel_hi:[1,0]
	v_exp_f32_e32 v20, v20
	v_exp_f32_e32 v21, v21
	v_exp_f32_e32 v22, v22
	v_exp_f32_e32 v23, v23
	v_pk_add_f32 v[20:21], v[20:21], 1.0 op_sel_hi:[1,0]
	v_pk_add_f32 v[22:23], v[22:23], 1.0 op_sel_hi:[1,0]
	v_rcp_f32_e32 v20, v20
	v_rcp_f32_e32 v21, v21
	v_rcp_f32_e32 v22, v22
	v_rcp_f32_e32 v23, v23
	v_pk_mul_f32 v[20:21], v[20:21], v[134:135] op_sel_hi:[1,0]
	v_pk_mul_f32 v[22:23], v[22:23], v[134:135] op_sel_hi:[1,0]
	v_pk_mul_f32 v[28:29], v[28:29], v[20:21]
	v_pk_mul_f32 v[30:31], v[30:31], v[22:23]
	v_cvt_pk_bf16_f32 v20, v28, v29
	v_cvt_pk_bf16_f32 v21, v30, v31
	v_pk_mul_f32 v[24:25], v[16:17], v[24:25]
	v_pk_mul_f32 v[16:17], v[16:17], v[132:133] op_sel_hi:[1,0]
	v_pk_mul_f32 v[26:27], v[18:19], v[26:27]
	v_pk_mul_f32 v[18:19], v[18:19], v[132:133] op_sel_hi:[1,0]
	v_exp_f32_e32 v16, v16
	v_exp_f32_e32 v17, v17
	v_exp_f32_e32 v18, v18
	v_exp_f32_e32 v19, v19
	v_pk_add_f32 v[16:17], v[16:17], 1.0 op_sel_hi:[1,0]
	v_pk_add_f32 v[18:19], v[18:19], 1.0 op_sel_hi:[1,0]
	v_rcp_f32_e32 v16, v16
	v_rcp_f32_e32 v17, v17
	v_rcp_f32_e32 v18, v18
	v_rcp_f32_e32 v19, v19
	v_pk_mul_f32 v[16:17], v[16:17], v[134:135] op_sel_hi:[1,0]
	v_pk_mul_f32 v[18:19], v[18:19], v[134:135] op_sel_hi:[1,0]
	v_pk_mul_f32 v[24:25], v[24:25], v[16:17]
	v_pk_mul_f32 v[26:27], v[26:27], v[18:19]
	v_cvt_pk_bf16_f32 v22, v24, v25
	v_cvt_pk_bf16_f32 v23, v26, v27
	s_nop 1
	v_permlane16_swap_b32_e32 v20, v22
	v_permlane16_swap_b32_e32 v21, v23
	global_store_dwordx4 v133, v[20:23], s[14:15]
	v_add_u32_e32 v133, 0x1d9000, v135
	v_mul_f32_e32 v132, 0xbfb8aa3b, v153
	v_mul_f32_e32 v134, v153, v153
	v_pk_mul_f32 v[12:13], v[4:5], v[12:13]
	v_pk_mul_f32 v[4:5], v[4:5], v[132:133] op_sel_hi:[1,0]
	v_pk_mul_f32 v[14:15], v[6:7], v[14:15]
	v_pk_mul_f32 v[6:7], v[6:7], v[132:133] op_sel_hi:[1,0]
	v_exp_f32_e32 v4, v4
	v_exp_f32_e32 v5, v5
	v_exp_f32_e32 v6, v6
	v_exp_f32_e32 v7, v7
	v_pk_add_f32 v[4:5], v[4:5], 1.0 op_sel_hi:[1,0]
	v_pk_add_f32 v[6:7], v[6:7], 1.0 op_sel_hi:[1,0]
	v_rcp_f32_e32 v4, v4
	v_rcp_f32_e32 v5, v5
	v_rcp_f32_e32 v6, v6
	v_rcp_f32_e32 v7, v7
	v_pk_mul_f32 v[4:5], v[4:5], v[134:135] op_sel_hi:[1,0]
	v_pk_mul_f32 v[6:7], v[6:7], v[134:135] op_sel_hi:[1,0]
	v_pk_mul_f32 v[12:13], v[12:13], v[4:5]
	v_pk_mul_f32 v[14:15], v[14:15], v[6:7]
	v_cvt_pk_bf16_f32 v4, v12, v13
	v_cvt_pk_bf16_f32 v5, v14, v15
	v_pk_mul_f32 v[8:9], v[0:1], v[8:9]
	v_pk_mul_f32 v[0:1], v[0:1], v[132:133] op_sel_hi:[1,0]
	v_pk_mul_f32 v[10:11], v[2:3], v[10:11]
	v_pk_mul_f32 v[2:3], v[2:3], v[132:133] op_sel_hi:[1,0]
	v_exp_f32_e32 v0, v0
	v_exp_f32_e32 v1, v1
	v_exp_f32_e32 v2, v2
	v_exp_f32_e32 v3, v3
	v_pk_add_f32 v[0:1], v[0:1], 1.0 op_sel_hi:[1,0]
	v_pk_add_f32 v[2:3], v[2:3], 1.0 op_sel_hi:[1,0]
	v_rcp_f32_e32 v0, v0
	v_rcp_f32_e32 v1, v1
	v_rcp_f32_e32 v2, v2
	v_rcp_f32_e32 v3, v3
	v_pk_mul_f32 v[0:1], v[0:1], v[134:135] op_sel_hi:[1,0]
	v_pk_mul_f32 v[2:3], v[2:3], v[134:135] op_sel_hi:[1,0]
	v_pk_mul_f32 v[8:9], v[8:9], v[0:1]
	v_pk_mul_f32 v[10:11], v[10:11], v[2:3]
	v_cvt_pk_bf16_f32 v6, v8, v9
	v_cvt_pk_bf16_f32 v7, v10, v11
	s_nop 1
	v_permlane16_swap_b32_e32 v4, v6
	v_permlane16_swap_b32_e32 v5, v7
	global_store_dwordx4 v133, v[4:7], s[14:15]
	s_waitcnt vmcnt(8)
	s_waitcnt vmcnt(8)
	v_add_f32_e32 v148, 0, v131
	s_barrier
	s_and_saveexec_b64 s[48:49], s[54:55]
	s_cbranch_execz .LBB0_766
	v_add_f32_e32 v0, v141, v148
	v_add_f32_e32 v0, v140, v0
	v_add_f32_e32 v0, v139, v0
	v_add_f32_e32 v0, v138, v0
	v_add_f32_e32 v0, v137, v0
	v_add_f32_e32 v0, v136, v0
	v_add_f32_e32 v0, v128, v0
	v_fmamk_f32 v0, v0, 0x3a000000, v143
	v_mul_f32_e32 v1, 0x4b800000, v0
	v_cmp_gt_f32_e32 vcc, s73, v0
	s_nop 1
	v_cndmask_b32_e32 v0, v0, v1, vcc
	v_rsq_f32_e32 v0, v0
	v_lshl_add_u32 v1, v130, 2, 0
	v_add_u32_e32 v1, 0x20000, v1
	v_mul_f32_e32 v2, 0x45800000, v0
	v_cndmask_b32_e32 v0, v0, v2, vcc
	ds_write_b32 v1, v0
	s_branch .LBB0_766

; __device__ __forceinline__ u16 f2bf(float x) { return (u16)(cvtpk(x, x) & 0xffffu); }
; #define UNR _Pragma("unroll")
; template <int EPI, int lda, int ldb, int N, int K>
; __device__ __forceinline__ void gemm_phase(const u16* __restrict__ A, const u16* __restrict__ Bt, const GemmEpi ep, int wv) {
;     ...
;     if constexpr (EPI == EPI_SWIGLU) {
;       u16* out = reinterpret_cast<u16*>(ep.out0);
;       UNR for (int ai = 0; ai < 2; ++ai) UNR for (int m = 0; m < 4; ++m) {
;         const int rl0 = ai * HALF + wr * 64 + m * 16 + fq * 4;
;         const f32x4 r4 = *reinterpret_cast<const f32x4*>(lrs + rl0);
;         UNR for (int j = 0; j < 4; ++j) {
;           const int row = brow + rl0 + j;
;           const float rs = r4[j], ce = -1.4426950408889634f * rs, r2 = rs * rs;
;           UNR for (int n = 0; n < 2; ++n) {
;             const int col = (bcol >> 1) + wc * 32 + n * 16 + fr;
;             const float g = acc[ai][0][m][n][j], u = acc[ai][1][m][n][j];
;             const float sg = __builtin_amdgcn_rcpf(1.f + __builtin_amdgcn_exp2f(ce * g));
;             out[(size_t)row * ep.ldc + col] = f2bf((g * u) * (r2 * sg));
;           }
;         }
;       }
.LBB0_1571:
	s_or_b64 exec, exec, s[46:47]
	v_and_b32_e32 v132, 15, v130
	v_lshrrev_b32_e32 v134, 8, v130
	v_lshl_add_u32 v132, v134, 6, v132
	v_lshlrev_b32_e32 v149, 2, v132
	v_add_u32_e32 v149, 0x20000, v149
	ds_read_b32 v150, v149 offset:0
	ds_read_b32 v151, v149 offset:64
	ds_read_b32 v152, v149 offset:128
	ds_read_b32 v153, v149 offset:192
	v_add_u32_e32 v132, s38, v132
	v_mul_u32_u24_e32 v135, 0x2b00, v132
	v_bfe_u32 v134, v130, 6, 2
	v_lshlrev_b32_e32 v134, 5, v134
	v_bfe_u32 v132, v130, 4, 1
	v_lshl_add_u32 v134, v132, 4, v134
	v_bfe_u32 v132, v130, 5, 1
	v_lshl_add_u32 v134, v132, 3, v134
	v_lshrrev_b32_e64 v132, 1, s39
	v_add_u32_e32 v134, v132, v134
	v_lshl_add_u32 v135, v134, 1, v135
	s_waitcnt lgkmcnt(0)
	v_mul_f32_e32 v132, 0xbfb8aa3b, v150
	v_mul_f32_e32 v134, v150, v150
	ds_read_b32 v150, v149 offset:512
	v_pk_mul_f32 v[124:125], v[116:117], v[124:125]
	v_pk_mul_f32 v[116:117], v[116:117], v[132:133] op_sel_hi:[1,0]
	v_pk_mul_f32 v[126:127], v[118:119], v[126:127]
	v_pk_mul_f32 v[118:119], v[118:119], v[132:133] op_sel_hi:[1,0]
	v_exp_f32_e32 v116, v116
	v_exp_f32_e32 v117, v117
	v_exp_f32_e32 v118, v118
	v_exp_f32_e32 v119, v119
	v_pk_add_f32 v[116:117], v[116:117], 1.0 op_sel_hi:[1,0]
	v_pk_add_f32 v[118:119], v[118:119], 1.0 op_sel_hi:[1,0]
	v_rcp_f32_e32 v116, v116
	v_rcp_f32_e32 v117, v117
	v_rcp_f32_e32 v118, v118
	v_rcp_f32_e32 v119, v119
	v_pk_mul_f32 v[116:117], v[116:117], v[134:135] op_sel_hi:[1,0]
	v_pk_mul_f32 v[118:119], v[118:119], v[134:135] op_sel_hi:[1,0]
	v_pk_mul_f32 v[124:125], v[124:125], v[116:117]
	v_pk_mul_f32 v[126:127], v[126:127], v[118:119]
	v_cvt_pk_bf16_f32 v116, v124, v125
	v_cvt_pk_bf16_f32 v117, v126, v127
	v_pk_mul_f32 v[120:121], v[112:113], v[120:121]
	v_pk_mul_f32 v[112:113], v[112:113], v[132:133] op_sel_hi:[1,0]
	v_pk_mul_f32 v[122:123], v[114:115], v[122:123]
	v_pk_mul_f32 v[114:115], v[114:115], v[132:133] op_sel_hi:[1,0]
	v_exp_f32_e32 v112, v112
	v_exp_f32_e32 v113, v113
	v_exp_f32_e32 v114, v114
	v_exp_f32_e32 v115, v115
	v_pk_add_f32 v[112:113], v[112:113], 1.0 op_sel_hi:[1,0]
	v_pk_add_f32 v[114:115], v[114:115], 1.0 op_sel_hi:[1,0]
	v_rcp_f32_e32 v112, v112
	v_rcp_f32_e32 v113, v113
	v_rcp_f32_e32 v114, v114
	v_rcp_f32_e32 v115, v115
	v_pk_mul_f32 v[112:113], v[112:113], v[134:135] op_sel_hi:[1,0]
	v_pk_mul_f32 v[114:115], v[114:115], v[134:135] op_sel_hi:[1,0]
	v_pk_mul_f32 v[120:121], v[120:121], v[112:113]
	v_pk_mul_f32 v[122:123], v[122:123], v[114:115]
	v_cvt_pk_bf16_f32 v118, v120, v121
	v_cvt_pk_bf16_f32 v119, v122, v123
	s_nop 1
	v_permlane16_swap_b32_e32 v116, v118
	v_permlane16_swap_b32_e32 v117, v119
	global_store_dwordx4 v135, v[116:119], s[10:11]
	v_add_u32_e32 v133, 0x2b000, v135
	v_mul_f32_e32 v132, 0xbfb8aa3b, v151
	v_mul_f32_e32 v134, v151, v151
	ds_read_b32 v151, v149 offset:576
	v_pk_mul_f32 v[108:109], v[100:101], v[108:109]
	v_pk_mul_f32 v[100:101], v[100:101], v[132:133] op_sel_hi:[1,0]
	v_pk_mul_f32 v[110:111], v[102:103], v[110:111]
	v_pk_mul_f32 v[102:103], v[102:103], v[132:133] op_sel_hi:[1,0]
	v_exp_f32_e32 v100, v100
	v_exp_f32_e32 v101, v101
	v_exp_f32_e32 v102, v102
	v_exp_f32_e32 v103, v103
	v_pk_add_f32 v[100:101], v[100:101], 1.0 op_sel_hi:[1,0]
	v_pk_add_f32 v[102:103], v[102:103], 1.0 op_sel_hi:[1,0]
	v_rcp_f32_e32 v100, v100
	v_rcp_f32_e32 v101, v101
	v_rcp_f32_e32 v102, v102
	v_rcp_f32_e32 v103, v103
	v_pk_mul_f32 v[100:101], v[100:101], v[134:135] op_sel_hi:[1,0]
	v_pk_mul_f32 v[102:103], v[102:103], v[134:135] op_sel_hi:[1,0]
	v_pk_mul_f32 v[108:109], v[108:109], v[100:101]
	v_pk_mul_f32 v[110:111], v[110:111], v[102:103]
	v_cvt_pk_bf16_f32 v100, v108, v109
	v_cvt_pk_bf16_f32 v101, v110, v111
	v_pk_mul_f32 v[104:105], v[96:97], v[104:105]
	v_pk_mul_f32 v[96:97], v[96:97], v[132:133] op_sel_hi:[1,0]
	v_pk_mul_f32 v[106:107], v[98:99], v[106:107]
	v_pk_mul_f32 v[98:99], v[98:99], v[132:133] op_sel_hi:[1,0]
	v_exp_f32_e32 v96, v96
	v_exp_f32_e32 v97, v97
	v_exp_f32_e32 v98, v98
	v_exp_f32_e32 v99, v99
	v_pk_add_f32 v[96:97], v[96:97], 1.0 op_sel_hi:[1,0]
	v_pk_add_f32 v[98:99], v[98:99], 1.0 op_sel_hi:[1,0]
	v_rcp_f32_e32 v96, v96
	v_rcp_f32_e32 v97, v97
	v_rcp_f32_e32 v98, v98
	v_rcp_f32_e32 v99, v99
	v_pk_mul_f32 v[96:97], v[96:97], v[134:135] op_sel_hi:[1,0]
	v_pk_mul_f32 v[98:99], v[98:99], v[134:135] op_sel_hi:[1,0]
	v_pk_mul_f32 v[104:105], v[104:105], v[96:97]
	v_pk_mul_f32 v[106:107], v[106:107], v[98:99]
	v_cvt_pk_bf16_f32 v102, v104, v105
	v_cvt_pk_bf16_f32 v103, v106, v107
	s_nop 1
	v_permlane16_swap_b32_e32 v100, v102
	v_permlane16_swap_b32_e32 v101, v103
	global_store_dwordx4 v133, v[100:103], s[10:11]
	v_add_u32_e32 v133, 0x56000, v135
	v_mul_f32_e32 v132, 0xbfb8aa3b, v152
	v_mul_f32_e32 v134, v152, v152
	ds_read_b32 v152, v149 offset:640
	v_pk_mul_f32 v[92:93], v[84:85], v[92:93]
	v_pk_mul_f32 v[84:85], v[84:85], v[132:133] op_sel_hi:[1,0]
	v_pk_mul_f32 v[94:95], v[86:87], v[94:95]
	v_pk_mul_f32 v[86:87], v[86:87], v[132:133] op_sel_hi:[1,0]
	v_exp_f32_e32 v84, v84
	v_exp_f32_e32 v85, v85
	v_exp_f32_e32 v86, v86
	v_exp_f32_e32 v87, v87
	v_pk_add_f32 v[84:85], v[84:85], 1.0 op_sel_hi:[1,0]
	v_pk_add_f32 v[86:87], v[86:87], 1.0 op_sel_hi:[1,0]
	v_rcp_f32_e32 v84, v84
	v_rcp_f32_e32 v85, v85
	v_rcp_f32_e32 v86, v86
	v_rcp_f32_e32 v87, v87
	v_pk_mul_f32 v[84:85], v[84:85], v[134:135] op_sel_hi:[1,0]
	v_pk_mul_f32 v[86:87], v[86:87], v[134:135] op_sel_hi:[1,0]
	v_pk_mul_f32 v[92:93], v[92:93], v[84:85]
	v_pk_mul_f32 v[94:95], v[94:95], v[86:87]
	v_cvt_pk_bf16_f32 v84, v92, v93
	v_cvt_pk_bf16_f32 v85, v94, v95
	v_pk_mul_f32 v[88:89], v[80:81], v[88:89]
	v_pk_mul_f32 v[80:81], v[80:81], v[132:133] op_sel_hi:[1,0]
; __device__ __forceinline__ u16 f2bf(float x) { return (u16)(cvtpk(x, x) & 0xffffu); }
; #define UNR _Pragma("unroll")
; template <int EPI, int lda, int ldb, int N, int K>
; __device__ __forceinline__ void gemm_phase(const u16* __restrict__ A, const u16* __restrict__ Bt, const GemmEpi ep, int wv) {
;     ...
;       UNR for (int ai = 0; ai < 2; ++ai) UNR for (int m = 0; m < 4; ++m) {
;         const int rl0 = ai * HALF + wr * 64 + m * 16 + fq * 4;
;         const f32x4 r4 = *reinterpret_cast<const f32x4*>(lrs + rl0);
;         UNR for (int j = 0; j < 4; ++j) {
;           const int row = brow + rl0 + j;
;           const float rs = r4[j], ce = -1.4426950408889634f * rs, r2 = rs * rs;
;           UNR for (int n = 0; n < 2; ++n) {
;             const int col = (bcol >> 1) + wc * 32 + n * 16 + fr;
;             const float g = acc[ai][0][m][n][j], u = acc[ai][1][m][n][j];
;             const float sg = __builtin_amdgcn_rcpf(1.f + __builtin_amdgcn_exp2f(ce * g));
;             out[(size_t)row * ep.ldc + col] = f2bf((g * u) * (r2 * sg));
;           }
;         }
;       }
	v_pk_mul_f32 v[90:91], v[82:83], v[90:91]
	v_pk_mul_f32 v[82:83], v[82:83], v[132:133] op_sel_hi:[1,0]
	v_exp_f32_e32 v80, v80
	v_exp_f32_e32 v81, v81
	v_exp_f32_e32 v82, v82
	v_exp_f32_e32 v83, v83
	v_pk_add_f32 v[80:81], v[80:81], 1.0 op_sel_hi:[1,0]
	v_pk_add_f32 v[82:83], v[82:83], 1.0 op_sel_hi:[1,0]
	v_rcp_f32_e32 v80, v80
	v_rcp_f32_e32 v81, v81
	v_rcp_f32_e32 v82, v82
	v_rcp_f32_e32 v83, v83
	v_pk_mul_f32 v[80:81], v[80:81], v[134:135] op_sel_hi:[1,0]
	v_pk_mul_f32 v[82:83], v[82:83], v[134:135] op_sel_hi:[1,0]
	v_pk_mul_f32 v[88:89], v[88:89], v[80:81]
	v_pk_mul_f32 v[90:91], v[90:91], v[82:83]
	v_cvt_pk_bf16_f32 v86, v88, v89
	v_cvt_pk_bf16_f32 v87, v90, v91
	s_nop 1
	v_permlane16_swap_b32_e32 v84, v86
	v_permlane16_swap_b32_e32 v85, v87
	global_store_dwordx4 v133, v[84:87], s[10:11]
	v_add_u32_e32 v133, 0x81000, v135
	v_mul_f32_e32 v132, 0xbfb8aa3b, v153
	v_mul_f32_e32 v134, v153, v153
	ds_read_b32 v153, v149 offset:704
	v_pk_mul_f32 v[76:77], v[68:69], v[76:77]
	v_pk_mul_f32 v[68:69], v[68:69], v[132:133] op_sel_hi:[1,0]
	v_pk_mul_f32 v[78:79], v[70:71], v[78:79]
	v_pk_mul_f32 v[70:71], v[70:71], v[132:133] op_sel_hi:[1,0]
	v_exp_f32_e32 v68, v68
	v_exp_f32_e32 v69, v69
	v_exp_f32_e32 v70, v70
	v_exp_f32_e32 v71, v71
	v_pk_add_f32 v[68:69], v[68:69], 1.0 op_sel_hi:[1,0]
	v_pk_add_f32 v[70:71], v[70:71], 1.0 op_sel_hi:[1,0]
	v_rcp_f32_e32 v68, v68
	v_rcp_f32_e32 v69, v69
	v_rcp_f32_e32 v70, v70
	v_rcp_f32_e32 v71, v71
	v_pk_mul_f32 v[68:69], v[68:69], v[134:135] op_sel_hi:[1,0]
	v_pk_mul_f32 v[70:71], v[70:71], v[134:135] op_sel_hi:[1,0]
	v_pk_mul_f32 v[76:77], v[76:77], v[68:69]
	v_pk_mul_f32 v[78:79], v[78:79], v[70:71]
	v_cvt_pk_bf16_f32 v68, v76, v77
	v_cvt_pk_bf16_f32 v69, v78, v79
	v_pk_mul_f32 v[72:73], v[64:65], v[72:73]
	v_pk_mul_f32 v[64:65], v[64:65], v[132:133] op_sel_hi:[1,0]
	v_pk_mul_f32 v[74:75], v[66:67], v[74:75]
	v_pk_mul_f32 v[66:67], v[66:67], v[132:133] op_sel_hi:[1,0]
	v_exp_f32_e32 v64, v64
	v_exp_f32_e32 v65, v65
	v_exp_f32_e32 v66, v66
	v_exp_f32_e32 v67, v67
	v_pk_add_f32 v[64:65], v[64:65], 1.0 op_sel_hi:[1,0]
	v_pk_add_f32 v[66:67], v[66:67], 1.0 op_sel_hi:[1,0]
	v_rcp_f32_e32 v64, v64
	v_rcp_f32_e32 v65, v65
	v_rcp_f32_e32 v66, v66
	v_rcp_f32_e32 v67, v67
	v_pk_mul_f32 v[64:65], v[64:65], v[134:135] op_sel_hi:[1,0]
	v_pk_mul_f32 v[66:67], v[66:67], v[134:135] op_sel_hi:[1,0]
	v_pk_mul_f32 v[72:73], v[72:73], v[64:65]
	v_pk_mul_f32 v[74:75], v[74:75], v[66:67]
	v_cvt_pk_bf16_f32 v70, v72, v73
	v_cvt_pk_bf16_f32 v71, v74, v75
	s_nop 1
	v_permlane16_swap_b32_e32 v68, v70
	v_permlane16_swap_b32_e32 v69, v71
	global_store_dwordx4 v133, v[68:71], s[10:11]
	s_waitcnt lgkmcnt(0)
	v_add_u32_e32 v133, 0x158000, v135
	v_mul_f32_e32 v132, 0xbfb8aa3b, v150
	v_mul_f32_e32 v134, v150, v150
	v_pk_mul_f32 v[60:61], v[52:53], v[60:61]
	v_pk_mul_f32 v[52:53], v[52:53], v[132:133] op_sel_hi:[1,0]
	v_pk_mul_f32 v[62:63], v[54:55], v[62:63]
	v_pk_mul_f32 v[54:55], v[54:55], v[132:133] op_sel_hi:[1,0]
	v_exp_f32_e32 v52, v52
	v_exp_f32_e32 v53, v53
	v_exp_f32_e32 v54, v54
	v_exp_f32_e32 v55, v55
	v_pk_add_f32 v[52:53], v[52:53], 1.0 op_sel_hi:[1,0]
	v_pk_add_f32 v[54:55], v[54:55], 1.0 op_sel_hi:[1,0]
	v_rcp_f32_e32 v52, v52
	v_rcp_f32_e32 v53, v53
	v_rcp_f32_e32 v54, v54
	v_rcp_f32_e32 v55, v55
	v_pk_mul_f32 v[52:53], v[52:53], v[134:135] op_sel_hi:[1,0]
	v_pk_mul_f32 v[54:55], v[54:55], v[134:135] op_sel_hi:[1,0]
	v_pk_mul_f32 v[60:61], v[60:61], v[52:53]
	v_pk_mul_f32 v[62:63], v[62:63], v[54:55]
	v_cvt_pk_bf16_f32 v52, v60, v61
	v_cvt_pk_bf16_f32 v53, v62, v63
	v_pk_mul_f32 v[56:57], v[48:49], v[56:57]
	v_pk_mul_f32 v[48:49], v[48:49], v[132:133] op_sel_hi:[1,0]
	v_pk_mul_f32 v[58:59], v[50:51], v[58:59]
	v_pk_mul_f32 v[50:51], v[50:51], v[132:133] op_sel_hi:[1,0]
	v_exp_f32_e32 v48, v48
	v_exp_f32_e32 v49, v49
	v_exp_f32_e32 v50, v50
	v_exp_f32_e32 v51, v51
	v_pk_add_f32 v[48:49], v[48:49], 1.0 op_sel_hi:[1,0]
	v_pk_add_f32 v[50:51], v[50:51], 1.0 op_sel_hi:[1,0]
	v_rcp_f32_e32 v48, v48
	v_rcp_f32_e32 v49, v49
	v_rcp_f32_e32 v50, v50
	v_rcp_f32_e32 v51, v51
	v_pk_mul_f32 v[48:49], v[48:49], v[134:135] op_sel_hi:[1,0]
	v_pk_mul_f32 v[50:51], v[50:51], v[134:135] op_sel_hi:[1,0]
	v_pk_mul_f32 v[56:57], v[56:57], v[48:49]
	v_pk_mul_f32 v[58:59], v[58:59], v[50:51]
	v_cvt_pk_bf16_f32 v54, v56, v57
	v_cvt_pk_bf16_f32 v55, v58, v59
	s_nop 1
	v_permlane16_swap_b32_e32 v52, v54
	v_permlane16_swap_b32_e32 v53, v55
	global_store_dwordx4 v133, v[52:55], s[10:11]
	v_add_u32_e32 v133, 0x183000, v135
	v_mul_f32_e32 v132, 0xbfb8aa3b, v151
	v_mul_f32_e32 v134, v151, v151
	v_pk_mul_f32 v[44:45], v[36:37], v[44:45]
	v_pk_mul_f32 v[36:37], v[36:37], v[132:133] op_sel_hi:[1,0]
	v_pk_mul_f32 v[46:47], v[38:39], v[46:47]
	v_pk_mul_f32 v[38:39], v[38:39], v[132:133] op_sel_hi:[1,0]
	v_exp_f32_e32 v36, v36
	v_exp_f32_e32 v37, v37
	v_exp_f32_e32 v38, v38
	v_exp_f32_e32 v39, v39
	v_pk_add_f32 v[36:37], v[36:37], 1.0 op_sel_hi:[1,0]
	v_pk_add_f32 v[38:39], v[38:39], 1.0 op_sel_hi:[1,0]
	v_rcp_f32_e32 v36, v36
	v_rcp_f32_e32 v37, v37
	v_rcp_f32_e32 v38, v38
	v_rcp_f32_e32 v39, v39
	v_pk_mul_f32 v[36:37], v[36:37], v[134:135] op_sel_hi:[1,0]
	v_pk_mul_f32 v[38:39], v[38:39], v[134:135] op_sel_hi:[1,0]
; __device__ __forceinline__ u16 f2bf(float x) { return (u16)(cvtpk(x, x) & 0xffffu); }
; #define UNR _Pragma("unroll")
; #define WAIT_V(n) asm volatile("s_waitcnt vmcnt(" #n ")" ::: "memory")
; template <int EPI, int lda, int ldb, int N, int K>
; __device__ __forceinline__ void gemm_phase(const u16* __restrict__ A, const u16* __restrict__ Bt, const GemmEpi ep, int wv) {
;     ...
;       UNR for (int ai = 0; ai < 2; ++ai) UNR for (int m = 0; m < 4; ++m) {
;         const int rl0 = ai * HALF + wr * 64 + m * 16 + fq * 4;
;         const f32x4 r4 = *reinterpret_cast<const f32x4*>(lrs + rl0);
;         UNR for (int j = 0; j < 4; ++j) {
;           const int row = brow + rl0 + j;
;           const float rs = r4[j], ce = -1.4426950408889634f * rs, r2 = rs * rs;
;           UNR for (int n = 0; n < 2; ++n) {
;             const int col = (bcol >> 1) + wc * 32 + n * 16 + fr;
;             const float g = acc[ai][0][m][n][j], u = acc[ai][1][m][n][j];
;             const float sg = __builtin_amdgcn_rcpf(1.f + __builtin_amdgcn_exp2f(ce * g));
;             out[(size_t)row * ep.ldc + col] = f2bf((g * u) * (r2 * sg));
;           }
;         }
;       }
;     ...
;     if constexpr (PF) {
;       WAIT_V(0);
;       __syncthreads();
;       if constexpr (CONS) { if (more && tidx < 256) { float sq = 0.f; UNR for (int pp = 0; pp < 8; ++pp) sq += nss[pp];
;         lrs[tidx] = rsqrtf(sq * (1.f / DM) + 1e-6f); } }
;       if (!more) break;
	v_pk_mul_f32 v[44:45], v[44:45], v[36:37]
	v_pk_mul_f32 v[46:47], v[46:47], v[38:39]
	v_cvt_pk_bf16_f32 v36, v44, v45
	v_cvt_pk_bf16_f32 v37, v46, v47
	v_pk_mul_f32 v[40:41], v[32:33], v[40:41]
	v_pk_mul_f32 v[32:33], v[32:33], v[132:133] op_sel_hi:[1,0]
	v_pk_mul_f32 v[42:43], v[34:35], v[42:43]
	v_pk_mul_f32 v[34:35], v[34:35], v[132:133] op_sel_hi:[1,0]
	v_exp_f32_e32 v32, v32
	v_exp_f32_e32 v33, v33
	v_exp_f32_e32 v34, v34
	v_exp_f32_e32 v35, v35
	v_pk_add_f32 v[32:33], v[32:33], 1.0 op_sel_hi:[1,0]
	v_pk_add_f32 v[34:35], v[34:35], 1.0 op_sel_hi:[1,0]
	v_rcp_f32_e32 v32, v32
	v_rcp_f32_e32 v33, v33
	v_rcp_f32_e32 v34, v34
	v_rcp_f32_e32 v35, v35
	v_pk_mul_f32 v[32:33], v[32:33], v[134:135] op_sel_hi:[1,0]
	v_pk_mul_f32 v[34:35], v[34:35], v[134:135] op_sel_hi:[1,0]
	v_pk_mul_f32 v[40:41], v[40:41], v[32:33]
	v_pk_mul_f32 v[42:43], v[42:43], v[34:35]
	v_cvt_pk_bf16_f32 v38, v40, v41
	v_cvt_pk_bf16_f32 v39, v42, v43
	s_nop 1
	v_permlane16_swap_b32_e32 v36, v38
	v_permlane16_swap_b32_e32 v37, v39
	global_store_dwordx4 v133, v[36:39], s[10:11]
	v_add_u32_e32 v133, 0x1ae000, v135
	v_mul_f32_e32 v132, 0xbfb8aa3b, v152
	v_mul_f32_e32 v134, v152, v152
	v_pk_mul_f32 v[28:29], v[20:21], v[28:29]
	v_pk_mul_f32 v[20:21], v[20:21], v[132:133] op_sel_hi:[1,0]
	v_pk_mul_f32 v[30:31], v[22:23], v[30:31]
	v_pk_mul_f32 v[22:23], v[22:23], v[132:133] op_sel_hi:[1,0]
	v_exp_f32_e32 v20, v20
	v_exp_f32_e32 v21, v21
	v_exp_f32_e32 v22, v22
	v_exp_f32_e32 v23, v23
	v_pk_add_f32 v[20:21], v[20:21], 1.0 op_sel_hi:[1,0]
	v_pk_add_f32 v[22:23], v[22:23], 1.0 op_sel_hi:[1,0]
	v_rcp_f32_e32 v20, v20
	v_rcp_f32_e32 v21, v21
	v_rcp_f32_e32 v22, v22
	v_rcp_f32_e32 v23, v23
	v_pk_mul_f32 v[20:21], v[20:21], v[134:135] op_sel_hi:[1,0]
	v_pk_mul_f32 v[22:23], v[22:23], v[134:135] op_sel_hi:[1,0]
	v_pk_mul_f32 v[28:29], v[28:29], v[20:21]
	v_pk_mul_f32 v[30:31], v[30:31], v[22:23]
	v_cvt_pk_bf16_f32 v20, v28, v29
	v_cvt_pk_bf16_f32 v21, v30, v31
	v_pk_mul_f32 v[24:25], v[16:17], v[24:25]
	v_pk_mul_f32 v[16:17], v[16:17], v[132:133] op_sel_hi:[1,0]
	v_pk_mul_f32 v[26:27], v[18:19], v[26:27]
	v_pk_mul_f32 v[18:19], v[18:19], v[132:133] op_sel_hi:[1,0]
	v_exp_f32_e32 v16, v16
	v_exp_f32_e32 v17, v17
	v_exp_f32_e32 v18, v18
	v_exp_f32_e32 v19, v19
	v_pk_add_f32 v[16:17], v[16:17], 1.0 op_sel_hi:[1,0]
	v_pk_add_f32 v[18:19], v[18:19], 1.0 op_sel_hi:[1,0]
	v_rcp_f32_e32 v16, v16
	v_rcp_f32_e32 v17, v17
	v_rcp_f32_e32 v18, v18
	v_rcp_f32_e32 v19, v19
	v_pk_mul_f32 v[16:17], v[16:17], v[134:135] op_sel_hi:[1,0]
	v_pk_mul_f32 v[18:19], v[18:19], v[134:135] op_sel_hi:[1,0]
	v_pk_mul_f32 v[24:25], v[24:25], v[16:17]
	v_pk_mul_f32 v[26:27], v[26:27], v[18:19]
	v_cvt_pk_bf16_f32 v22, v24, v25
	v_cvt_pk_bf16_f32 v23, v26, v27
	s_nop 1
	v_permlane16_swap_b32_e32 v20, v22
	v_permlane16_swap_b32_e32 v21, v23
	global_store_dwordx4 v133, v[20:23], s[10:11]
	v_add_u32_e32 v133, 0x1d9000, v135
	v_mul_f32_e32 v132, 0xbfb8aa3b, v153
	v_mul_f32_e32 v134, v153, v153
	v_pk_mul_f32 v[12:13], v[4:5], v[12:13]
	v_pk_mul_f32 v[4:5], v[4:5], v[132:133] op_sel_hi:[1,0]
	v_pk_mul_f32 v[14:15], v[6:7], v[14:15]
	v_pk_mul_f32 v[6:7], v[6:7], v[132:133] op_sel_hi:[1,0]
	v_exp_f32_e32 v4, v4
	v_exp_f32_e32 v5, v5
	v_exp_f32_e32 v6, v6
	v_exp_f32_e32 v7, v7
	v_pk_add_f32 v[4:5], v[4:5], 1.0 op_sel_hi:[1,0]
	v_pk_add_f32 v[6:7], v[6:7], 1.0 op_sel_hi:[1,0]
	v_rcp_f32_e32 v4, v4
	v_rcp_f32_e32 v5, v5
	v_rcp_f32_e32 v6, v6
	v_rcp_f32_e32 v7, v7
	v_pk_mul_f32 v[4:5], v[4:5], v[134:135] op_sel_hi:[1,0]
	v_pk_mul_f32 v[6:7], v[6:7], v[134:135] op_sel_hi:[1,0]
	v_pk_mul_f32 v[12:13], v[12:13], v[4:5]
	v_pk_mul_f32 v[14:15], v[14:15], v[6:7]
	v_cvt_pk_bf16_f32 v4, v12, v13
	v_cvt_pk_bf16_f32 v5, v14, v15
	v_pk_mul_f32 v[8:9], v[0:1], v[8:9]
	v_pk_mul_f32 v[0:1], v[0:1], v[132:133] op_sel_hi:[1,0]
	v_pk_mul_f32 v[10:11], v[2:3], v[10:11]
	v_pk_mul_f32 v[2:3], v[2:3], v[132:133] op_sel_hi:[1,0]
	v_exp_f32_e32 v0, v0
	v_exp_f32_e32 v1, v1
	v_exp_f32_e32 v2, v2
	v_exp_f32_e32 v3, v3
	v_pk_add_f32 v[0:1], v[0:1], 1.0 op_sel_hi:[1,0]
	v_pk_add_f32 v[2:3], v[2:3], 1.0 op_sel_hi:[1,0]
	v_rcp_f32_e32 v0, v0
	v_rcp_f32_e32 v1, v1
	v_rcp_f32_e32 v2, v2
	v_rcp_f32_e32 v3, v3
	v_pk_mul_f32 v[0:1], v[0:1], v[134:135] op_sel_hi:[1,0]
	v_pk_mul_f32 v[2:3], v[2:3], v[134:135] op_sel_hi:[1,0]
	v_pk_mul_f32 v[8:9], v[8:9], v[0:1]
	v_pk_mul_f32 v[10:11], v[10:11], v[2:3]
	v_cvt_pk_bf16_f32 v6, v8, v9
	v_cvt_pk_bf16_f32 v7, v10, v11
	s_nop 1
	v_permlane16_swap_b32_e32 v4, v6
	v_permlane16_swap_b32_e32 v5, v7
	global_store_dwordx4 v133, v[4:7], s[10:11]
	s_waitcnt vmcnt(8)
	s_waitcnt vmcnt(8)
	v_add_f32_e32 v148, 0, v131
	s_barrier
	s_and_saveexec_b64 s[38:39], s[44:45]
	s_cbranch_execz .LBB0_1560
	v_add_f32_e32 v0, v141, v148
	v_add_f32_e32 v0, v140, v0
	v_add_f32_e32 v0, v139, v0
	v_add_f32_e32 v0, v138, v0
	v_add_f32_e32 v0, v137, v0
	v_add_f32_e32 v0, v136, v0
	v_add_f32_e32 v0, v128, v0
	v_fmamk_f32 v0, v0, 0x3a000000, v143
	v_mul_f32_e32 v1, 0x4b800000, v0
	v_cmp_gt_f32_e32 vcc, s61, v0
	s_nop 1
	v_cndmask_b32_e32 v0, v0, v1, vcc
	v_rsq_f32_e32 v0, v0
	v_lshl_add_u32 v1, v130, 2, 0
	v_add_u32_e32 v1, 0x20000, v1
	v_mul_f32_e32 v2, 0x45800000, v0
	v_cndmask_b32_e32 v0, v0, v2, vcc
	ds_write_b32 v1, v0
	s_branch .LBB0_1560
